# dilated core v3: QK^T MFMAs of block j+1 issued before block j's softmax (software pipelined, unrolled)
# speedup vs baseline: 1.0001x; 1.0001x over previous
.LBB0_461:
	s_ashr_i32 s10, s62, 6
	s_addk_i32 s62, 0xff80
	s_ashr_i32 s52, s62, 6
	s_max_i32 s54, s52, s59
	s_mov_b64 s[52:53], -1
	s_cmp_le_i32 s54, s10
	v_lshlrev_b32_e32 v157, 2, v69
	s_cbranch_scc0 .LBB0_470
	v_and_b32_e32 v50, 31, v153
	v_lshrrev_b32_e32 v51, 5, v153
	v_lshlrev_b32_e32 v132, 2, v51
	v_sub_u32_e32 v122, v50, v132
	v_lshrrev_b32_e32 v52, 1, v50
	v_and_b32_e32 v53, 6, v52
	v_lshlrev_b32_e32 v53, 4, v53
	v_and_b32_e32 v52, 1, v52
	v_xor_b32_e32 v52, v52, v51
	v_lshlrev_b32_e32 v52, 4, v52
	v_lshl_add_u32 v124, v50, 7, v53
	v_add_u32_e32 v124, v124, v52
	v_xor_b32_e32 v134, 32, v124
	v_xor_b32_e32 v135, 64, v124
	v_xor_b32_e32 v136, 0x60, v124
	v_bfe_u32 v52, v153, 4, 1
	v_lshlrev_b32_e32 v52, 5, v52
	v_and_b32_e32 v53, 3, v153
	v_lshl_add_u32 v52, v53, 3, v52
	v_bfe_u32 v53, v153, 2, 2
	v_add_u32_e32 v53, v53, v132
	v_lshl_add_u32 v125, v53, 6, v52
	s_add_i32 s62, s62, 0x80
	s_lshr_b32 s54, s62, 5
	s_sub_i32 s55, 4, s54
	s_max_i32 s55, s55, 0
	s_add_i32 s54, s54, -4
	s_add_i32 s52, s54, s55
	s_and_b32 s53, s52, 1
	s_lshr_b32 s52, s52, 1
	s_sub_i32 s52, s52, s59
	s_lshl_b32 s52, s52, 14
	s_lshl_b32 s53, s53, 12
	s_add_i32 s56, s53, s52
	v_add_u32_e32 v140, s56, v124
	v_add_u32_e32 v142, s56, v134
	v_add_u32_e32 v143, s56, v135
	v_add_u32_e32 v144, s56, v136
	ds_read_b128 v[50:53], v140
	ds_read_b128 v[54:57], v142
	ds_read_b128 v[58:61], v143
	ds_read_b128 v[62:65], v144
	s_add_i32 s61, s61, 1
	v_cvt_f32_i32_e32 v144, s61
	v_exp_f32_e64 v144, -v144
	s_lshl_b32 s53, 1, s60
	v_cvt_f32_ubyte0_e32 v145, s53
	s_nop 0
	v_mul_f32_e32 v144, v144, v145
	v_mul_f32_e32 v126, 0x3fb8aa3b, v144
	v_mov_b32_e32 v187, 0
	v_mov_b32_e32 v188, v126
	v_mul_f32_e32 v189, 0x40000000, v126
	v_mul_f32_e32 v190, 0x40400000, v126
	v_mul_f32_e32 v191, 0x41000000, v126
	v_mul_f32_e32 v192, 0x41100000, v126
	v_mul_f32_e32 v193, 0x41200000, v126
	v_mul_f32_e32 v194, 0x41300000, v126
	v_mul_f32_e32 v195, 0x41800000, v126
	v_mul_f32_e32 v196, 0x41880000, v126
	v_mul_f32_e32 v197, 0x41900000, v126
	v_mul_f32_e32 v198, 0x41980000, v126
	v_mul_f32_e32 v199, 0x41c00000, v126
	v_mul_f32_e32 v200, 0x41c80000, v126
	v_mul_f32_e32 v201, 0x41d00000, v126
	v_mul_f32_e32 v202, 0x41d80000, v126
	v_cmp_ge_i32_e64 s[52:53], 0, v122
	v_cmp_ge_i32_e64 s[56:57], 1, v122
	v_cmp_ge_i32_e64 s[62:63], 2, v122
	v_cmp_ge_i32_e64 s[10:11], 3, v122
	s_nop 1
	v_cndmask_b32_e64 v203, v177, v187, s[52:53]
	v_cndmask_b32_e64 v204, v177, v188, s[56:57]
	v_cndmask_b32_e64 v205, v177, v189, s[62:63]
	v_cndmask_b32_e64 v206, v177, v190, s[10:11]
	v_cmp_ge_i32_e64 s[52:53], 8, v122
	v_cmp_ge_i32_e64 s[56:57], 9, v122
	v_cmp_ge_i32_e64 s[62:63], 10, v122
	v_cmp_ge_i32_e64 s[10:11], 11, v122
	s_nop 1
	v_cndmask_b32_e64 v207, v177, v191, s[52:53]
	v_cndmask_b32_e64 v208, v177, v192, s[56:57]
	v_cndmask_b32_e64 v209, v177, v193, s[62:63]
	v_cndmask_b32_e64 v210, v177, v194, s[10:11]
	v_cmp_ge_i32_e64 s[52:53], 16, v122
	v_cmp_ge_i32_e64 s[56:57], 17, v122
	v_cmp_ge_i32_e64 s[62:63], 18, v122
	v_cmp_ge_i32_e64 s[10:11], 19, v122
	s_nop 1
	v_cndmask_b32_e64 v211, v177, v195, s[52:53]
	v_cndmask_b32_e64 v212, v177, v196, s[56:57]
	v_cndmask_b32_e64 v213, v177, v197, s[62:63]
	v_cndmask_b32_e64 v214, v177, v198, s[10:11]
	v_cmp_ge_i32_e64 s[52:53], 24, v122
	v_cmp_ge_i32_e64 s[56:57], 25, v122
	v_cmp_ge_i32_e64 s[62:63], 26, v122
	v_cmp_ge_i32_e64 s[10:11], 27, v122
	s_nop 1
	v_cndmask_b32_e64 v215, v177, v199, s[52:53]
	v_cndmask_b32_e64 v216, v177, v200, s[56:57]
	v_cndmask_b32_e64 v217, v177, v201, s[62:63]
	v_cndmask_b32_e64 v218, v177, v202, s[10:11]
	v_cmp_le_i32_e64 s[52:53], 0, v122
	v_cmp_le_i32_e64 s[56:57], 1, v122
	v_cmp_le_i32_e64 s[62:63], 2, v122
	v_cmp_le_i32_e64 s[10:11], 3, v122
	s_nop 1
	v_cndmask_b32_e64 v219, v177, v187, s[52:53]
	v_cndmask_b32_e64 v220, v177, v188, s[56:57]
	v_cndmask_b32_e64 v221, v177, v189, s[62:63]
	v_cndmask_b32_e64 v222, v177, v190, s[10:11]
	v_cmp_le_i32_e64 s[52:53], 8, v122
	v_cmp_le_i32_e64 s[56:57], 9, v122
	v_cmp_le_i32_e64 s[62:63], 10, v122
	v_cmp_le_i32_e64 s[10:11], 11, v122
	s_nop 1
	v_cndmask_b32_e64 v223, v177, v191, s[52:53]
	v_cndmask_b32_e64 v224, v177, v192, s[56:57]
	v_cndmask_b32_e64 v225, v177, v193, s[62:63]
	v_cndmask_b32_e64 v226, v177, v194, s[10:11]
	v_cmp_le_i32_e64 s[52:53], 16, v122
	v_cmp_le_i32_e64 s[56:57], 17, v122
	v_cmp_le_i32_e64 s[62:63], 18, v122
	v_cmp_le_i32_e64 s[10:11], 19, v122
	s_nop 1
	v_cndmask_b32_e64 v227, v177, v195, s[52:53]
	v_cndmask_b32_e64 v228, v177, v196, s[56:57]
	v_cndmask_b32_e64 v229, v177, v197, s[62:63]
	v_cndmask_b32_e64 v230, v177, v198, s[10:11]
	v_cmp_le_i32_e64 s[52:53], 24, v122
	v_cmp_le_i32_e64 s[56:57], 25, v122
	v_cmp_le_i32_e64 s[62:63], 26, v122
	v_cmp_le_i32_e64 s[10:11], 27, v122
	s_nop 1
	v_cndmask_b32_e64 v231, v177, v199, s[52:53]
	v_cndmask_b32_e64 v232, v177, v200, s[56:57]
	v_cndmask_b32_e64 v233, v177, v201, s[62:63]
	v_cndmask_b32_e64 v234, v177, v202, s[10:11]
	s_mov_b32 s11, 0
	v_mov_b32_e32 v2, 0
	v_mov_b32_e32 v3, 0
	v_mov_b32_e32 v4, 0
	v_mov_b32_e32 v5, 0
	v_mov_b32_e32 v6, 0
	v_mov_b32_e32 v7, 0
	v_mov_b32_e32 v8, 0
	v_mov_b32_e32 v9, 0
	v_mov_b32_e32 v10, 0
	v_mov_b32_e32 v11, 0
	v_mov_b32_e32 v12, 0
	v_mov_b32_e32 v13, 0
	v_mov_b32_e32 v14, 0
	v_mov_b32_e32 v15, 0
	v_mov_b32_e32 v16, 0
	v_mov_b32_e32 v17, 0
	v_mov_b32_e32 v18, 0
	v_mov_b32_e32 v19, 0
	v_mov_b32_e32 v20, 0
	v_mov_b32_e32 v21, 0
	v_mov_b32_e32 v22, 0
	v_mov_b32_e32 v23, 0
	v_mov_b32_e32 v24, 0
	v_mov_b32_e32 v25, 0
	v_mov_b32_e32 v26, 0
	v_mov_b32_e32 v27, 0
	v_mov_b32_e32 v28, 0
	v_mov_b32_e32 v29, 0
	v_mov_b32_e32 v30, 0
	v_mov_b32_e32 v31, 0
	v_mov_b32_e32 v32, 0
	v_mov_b32_e32 v33, 0
	v_mov_b32_e32 v138, 0
	v_mov_b32_e32 v139, 0
	s_mov_b32 s63, 1
	s_cmp_eq_u32 s55, 0
	s_cbranch_scc1 .Ld3_in0
	s_cmp_eq_u32 s55, 1
	s_cbranch_scc1 .Ld3_in1
	s_cmp_eq_u32 s55, 2
	s_cbranch_scc1 .Ld3_in2
	s_cmp_eq_u32 s55, 3
	s_cbranch_scc1 .Ld3_in3
	s_branch .Ld3_in4
.Ld3_in0:
	v_add_u32_e32 v140, 128, v122
	v_cvt_f32_i32_e32 v140, v140
	v_fma_f32 v123, -v126, v140, -v138
	v_add_f32_e32 v34, v203, v123
	v_add_f32_e32 v35, v204, v123
	v_add_f32_e32 v36, v205, v123
	v_add_f32_e32 v37, v206, v123
	v_add_f32_e32 v38, v207, v123
	v_add_f32_e32 v39, v208, v123
	v_add_f32_e32 v40, v209, v123
	v_add_f32_e32 v41, v210, v123
	v_add_f32_e32 v42, v211, v123
	v_add_f32_e32 v43, v212, v123
	v_add_f32_e32 v44, v213, v123
	v_add_f32_e32 v45, v214, v123
	v_add_f32_e32 v46, v215, v123
	v_add_f32_e32 v47, v216, v123
	v_add_f32_e32 v48, v217, v123
	v_add_f32_e32 v49, v218, v123
	s_waitcnt lgkmcnt(0)
	s_nop 1
	v_mfma_f32_32x32x16_bf16 v[34:49], v[50:53], v[82:85], v[34:49]
	v_mfma_f32_32x32x16_bf16 v[34:49], v[54:57], v[86:89], v[34:49]
	v_mfma_f32_32x32x16_bf16 v[34:49], v[58:61], v[90:93], v[34:49]
	v_mfma_f32_32x32x16_bf16 v[34:49], v[62:65], v[94:97], v[34:49]
	s_add_i32 s52, s54, 0
	s_and_b32 s53, s52, 1
	s_lshr_b32 s52, s52, 1
	s_sub_i32 s52, s52, s59
	s_lshl_b32 s52, s52, 14
	s_lshl_b32 s53, s53, 11
	s_add_i32 s53, s53, s52
	s_addk_i32 s53, 0x2000
	v_add_u32_e32 v141, s53, v125
	ds_read_b64_tr_b16 v[98:99], v141
	ds_read_b64_tr_b16 v[100:101], v141 offset:512
	ds_read_b64_tr_b16 v[102:103], v141 offset:1024
	ds_read_b64_tr_b16 v[104:105], v141 offset:1536
	ds_read_b64_tr_b16 v[106:107], v141 offset:4096
	ds_read_b64_tr_b16 v[108:109], v141 offset:4608
	ds_read_b64_tr_b16 v[110:111], v141 offset:5120
	ds_read_b64_tr_b16 v[112:113], v141 offset:5632
	s_add_i32 s52, s54, 1
	s_and_b32 s53, s52, 1
	s_lshr_b32 s52, s52, 1
	s_sub_i32 s52, s52, s59
	s_lshl_b32 s52, s52, 14
	s_lshl_b32 s53, s53, 12
	s_add_i32 s56, s53, s52
	v_add_u32_e32 v140, s56, v124
	v_add_u32_e32 v142, s56, v134
	v_add_u32_e32 v143, s56, v135
	v_add_u32_e32 v144, s56, v136
	ds_read_b128 v[50:53], v140
	ds_read_b128 v[54:57], v142
	ds_read_b128 v[58:61], v143
	ds_read_b128 v[62:65], v144
	s_branch .Ld3_b0
.Ld3_in1:
	v_add_u32_e32 v140, 96, v122
	v_cvt_f32_i32_e32 v140, v140
	v_fma_f32 v123, -v126, v140, -v138
	v_add_f32_e32 v158, v187, v123
	v_add_f32_e32 v159, v188, v123
	v_add_f32_e32 v160, v189, v123
	v_add_f32_e32 v161, v190, v123
	v_add_f32_e32 v162, v191, v123
	v_add_f32_e32 v163, v192, v123
	v_add_f32_e32 v164, v193, v123
	v_add_f32_e32 v165, v194, v123
	v_add_f32_e32 v166, v195, v123
	v_add_f32_e32 v167, v196, v123
	v_add_f32_e32 v168, v197, v123
	v_add_f32_e32 v169, v198, v123
	v_add_f32_e32 v170, v199, v123
	v_add_f32_e32 v171, v200, v123
	v_add_f32_e32 v172, v201, v123
	v_add_f32_e32 v173, v202, v123
	s_waitcnt lgkmcnt(0)
	s_nop 1
	v_mfma_f32_32x32x16_bf16 v[158:173], v[50:53], v[82:85], v[158:173]
	v_mfma_f32_32x32x16_bf16 v[158:173], v[54:57], v[86:89], v[158:173]
	v_mfma_f32_32x32x16_bf16 v[158:173], v[58:61], v[90:93], v[158:173]
	v_mfma_f32_32x32x16_bf16 v[158:173], v[62:65], v[94:97], v[158:173]
	s_add_i32 s52, s54, 1
	s_and_b32 s53, s52, 1
	s_lshr_b32 s52, s52, 1
	s_sub_i32 s52, s52, s59
	s_lshl_b32 s52, s52, 14
	s_lshl_b32 s53, s53, 11
	s_add_i32 s53, s53, s52
	s_addk_i32 s53, 0x2000
	v_add_u32_e32 v141, s53, v125
	ds_read_b64_tr_b16 v[98:99], v141
	ds_read_b64_tr_b16 v[100:101], v141 offset:512
	ds_read_b64_tr_b16 v[102:103], v141 offset:1024
	ds_read_b64_tr_b16 v[104:105], v141 offset:1536
	ds_read_b64_tr_b16 v[106:107], v141 offset:4096
	ds_read_b64_tr_b16 v[108:109], v141 offset:4608
	ds_read_b64_tr_b16 v[110:111], v141 offset:5120
	ds_read_b64_tr_b16 v[112:113], v141 offset:5632
	s_add_i32 s52, s54, 2
	s_and_b32 s53, s52, 1
	s_lshr_b32 s52, s52, 1
	s_sub_i32 s52, s52, s59
	s_lshl_b32 s52, s52, 14
	s_lshl_b32 s53, s53, 12
	s_add_i32 s56, s53, s52
	v_add_u32_e32 v140, s56, v124
	v_add_u32_e32 v142, s56, v134
	v_add_u32_e32 v143, s56, v135
	v_add_u32_e32 v144, s56, v136
	ds_read_b128 v[50:53], v140
	ds_read_b128 v[54:57], v142
	ds_read_b128 v[58:61], v143
	ds_read_b128 v[62:65], v144
	s_branch .Ld3_b1
.Ld3_in2:
	v_add_u32_e32 v140, 64, v122
	v_cvt_f32_i32_e32 v140, v140
	v_fma_f32 v123, -v126, v140, -v138
	v_add_f32_e32 v34, v187, v123
	v_add_f32_e32 v35, v188, v123
	v_add_f32_e32 v36, v189, v123
	v_add_f32_e32 v37, v190, v123
	v_add_f32_e32 v38, v191, v123
	v_add_f32_e32 v39, v192, v123
	v_add_f32_e32 v40, v193, v123
	v_add_f32_e32 v41, v194, v123
	v_add_f32_e32 v42, v195, v123
	v_add_f32_e32 v43, v196, v123
	v_add_f32_e32 v44, v197, v123
	v_add_f32_e32 v45, v198, v123
	v_add_f32_e32 v46, v199, v123
	v_add_f32_e32 v47, v200, v123
	v_add_f32_e32 v48, v201, v123
	v_add_f32_e32 v49, v202, v123
	s_waitcnt lgkmcnt(0)
	s_nop 1
	v_mfma_f32_32x32x16_bf16 v[34:49], v[50:53], v[82:85], v[34:49]
	v_mfma_f32_32x32x16_bf16 v[34:49], v[54:57], v[86:89], v[34:49]
	v_mfma_f32_32x32x16_bf16 v[34:49], v[58:61], v[90:93], v[34:49]
	v_mfma_f32_32x32x16_bf16 v[34:49], v[62:65], v[94:97], v[34:49]
	s_add_i32 s52, s54, 2
	s_and_b32 s53, s52, 1
	s_lshr_b32 s52, s52, 1
	s_sub_i32 s52, s52, s59
	s_lshl_b32 s52, s52, 14
	s_lshl_b32 s53, s53, 11
	s_add_i32 s53, s53, s52
	s_addk_i32 s53, 0x2000
	v_add_u32_e32 v141, s53, v125
	ds_read_b64_tr_b16 v[98:99], v141
	ds_read_b64_tr_b16 v[100:101], v141 offset:512
	ds_read_b64_tr_b16 v[102:103], v141 offset:1024
	ds_read_b64_tr_b16 v[104:105], v141 offset:1536
	ds_read_b64_tr_b16 v[106:107], v141 offset:4096
	ds_read_b64_tr_b16 v[108:109], v141 offset:4608
	ds_read_b64_tr_b16 v[110:111], v141 offset:5120
	ds_read_b64_tr_b16 v[112:113], v141 offset:5632
	s_add_i32 s52, s54, 3
	s_and_b32 s53, s52, 1
	s_lshr_b32 s52, s52, 1
	s_sub_i32 s52, s52, s59
	s_lshl_b32 s52, s52, 14
	s_lshl_b32 s53, s53, 12
	s_add_i32 s56, s53, s52
	v_add_u32_e32 v140, s56, v124
	v_add_u32_e32 v142, s56, v134
	v_add_u32_e32 v143, s56, v135
	v_add_u32_e32 v144, s56, v136
	ds_read_b128 v[50:53], v140
	ds_read_b128 v[54:57], v142
	ds_read_b128 v[58:61], v143
	ds_read_b128 v[62:65], v144
	s_branch .Ld3_b2
.Ld3_in3:
	v_add_u32_e32 v140, 32, v122
	v_cvt_f32_i32_e32 v140, v140
	v_fma_f32 v123, -v126, v140, -v138
	v_add_f32_e32 v158, v187, v123
	v_add_f32_e32 v159, v188, v123
	v_add_f32_e32 v160, v189, v123
	v_add_f32_e32 v161, v190, v123
	v_add_f32_e32 v162, v191, v123
	v_add_f32_e32 v163, v192, v123
	v_add_f32_e32 v164, v193, v123
	v_add_f32_e32 v165, v194, v123
	v_add_f32_e32 v166, v195, v123
	v_add_f32_e32 v167, v196, v123
	v_add_f32_e32 v168, v197, v123
	v_add_f32_e32 v169, v198, v123
	v_add_f32_e32 v170, v199, v123
	v_add_f32_e32 v171, v200, v123
	v_add_f32_e32 v172, v201, v123
	v_add_f32_e32 v173, v202, v123
	s_waitcnt lgkmcnt(0)
	s_nop 1
	v_mfma_f32_32x32x16_bf16 v[158:173], v[50:53], v[82:85], v[158:173]
	v_mfma_f32_32x32x16_bf16 v[158:173], v[54:57], v[86:89], v[158:173]
	v_mfma_f32_32x32x16_bf16 v[158:173], v[58:61], v[90:93], v[158:173]
	v_mfma_f32_32x32x16_bf16 v[158:173], v[62:65], v[94:97], v[158:173]
	s_add_i32 s52, s54, 3
	s_and_b32 s53, s52, 1
	s_lshr_b32 s52, s52, 1
	s_sub_i32 s52, s52, s59
	s_lshl_b32 s52, s52, 14
	s_lshl_b32 s53, s53, 11
	s_add_i32 s53, s53, s52
	s_addk_i32 s53, 0x2000
	v_add_u32_e32 v141, s53, v125
	ds_read_b64_tr_b16 v[98:99], v141
	ds_read_b64_tr_b16 v[100:101], v141 offset:512
	ds_read_b64_tr_b16 v[102:103], v141 offset:1024
	ds_read_b64_tr_b16 v[104:105], v141 offset:1536
	ds_read_b64_tr_b16 v[106:107], v141 offset:4096
	ds_read_b64_tr_b16 v[108:109], v141 offset:4608
	ds_read_b64_tr_b16 v[110:111], v141 offset:5120
	ds_read_b64_tr_b16 v[112:113], v141 offset:5632
	s_add_i32 s52, s54, 4
	s_and_b32 s53, s52, 1
	s_lshr_b32 s52, s52, 1
	s_sub_i32 s52, s52, s59
	s_lshl_b32 s52, s52, 14
	s_lshl_b32 s53, s53, 12
	s_add_i32 s56, s53, s52
	v_add_u32_e32 v140, s56, v124
	v_add_u32_e32 v142, s56, v134
	v_add_u32_e32 v143, s56, v135
	v_add_u32_e32 v144, s56, v136
	ds_read_b128 v[50:53], v140
	ds_read_b128 v[54:57], v142
	ds_read_b128 v[58:61], v143
	ds_read_b128 v[62:65], v144
	s_branch .Ld3_b3
.Ld3_in4:
	v_add_u32_e32 v140, 0, v122
	v_cvt_f32_i32_e32 v140, v140
	v_fma_f32 v123, -v126, v140, -v138
	v_add_f32_e32 v34, v219, v123
	v_add_f32_e32 v35, v220, v123
	v_add_f32_e32 v36, v221, v123
	v_add_f32_e32 v37, v222, v123
	v_add_f32_e32 v38, v223, v123
	v_add_f32_e32 v39, v224, v123
	v_add_f32_e32 v40, v225, v123
	v_add_f32_e32 v41, v226, v123
	v_add_f32_e32 v42, v227, v123
	v_add_f32_e32 v43, v228, v123
	v_add_f32_e32 v44, v229, v123
	v_add_f32_e32 v45, v230, v123
	v_add_f32_e32 v46, v231, v123
	v_add_f32_e32 v47, v232, v123
	v_add_f32_e32 v48, v233, v123
	v_add_f32_e32 v49, v234, v123
	s_waitcnt lgkmcnt(0)
	s_nop 1
	v_mfma_f32_32x32x16_bf16 v[34:49], v[50:53], v[82:85], v[34:49]
	v_mfma_f32_32x32x16_bf16 v[34:49], v[54:57], v[86:89], v[34:49]
	v_mfma_f32_32x32x16_bf16 v[34:49], v[58:61], v[90:93], v[34:49]
	v_mfma_f32_32x32x16_bf16 v[34:49], v[62:65], v[94:97], v[34:49]
	s_add_i32 s52, s54, 4
	s_and_b32 s53, s52, 1
	s_lshr_b32 s52, s52, 1
	s_sub_i32 s52, s52, s59
	s_lshl_b32 s52, s52, 14
	s_lshl_b32 s53, s53, 11
	s_add_i32 s53, s53, s52
	s_addk_i32 s53, 0x2000
	v_add_u32_e32 v141, s53, v125
	ds_read_b64_tr_b16 v[98:99], v141
	ds_read_b64_tr_b16 v[100:101], v141 offset:512
	ds_read_b64_tr_b16 v[102:103], v141 offset:1024
	ds_read_b64_tr_b16 v[104:105], v141 offset:1536
	ds_read_b64_tr_b16 v[106:107], v141 offset:4096
	ds_read_b64_tr_b16 v[108:109], v141 offset:4608
	ds_read_b64_tr_b16 v[110:111], v141 offset:5120
	ds_read_b64_tr_b16 v[112:113], v141 offset:5632
	s_branch .Ld3_b4
.Ld3_b0:
	v_add_u32_e32 v140, 96, v122
	v_cvt_f32_i32_e32 v140, v140
	v_fma_f32 v123, -v126, v140, -v138
	v_add_f32_e32 v158, v187, v123
	v_add_f32_e32 v159, v188, v123
	v_add_f32_e32 v160, v189, v123
	v_add_f32_e32 v161, v190, v123
	v_add_f32_e32 v162, v191, v123
	v_add_f32_e32 v163, v192, v123
	v_add_f32_e32 v164, v193, v123
	v_add_f32_e32 v165, v194, v123
	v_add_f32_e32 v166, v195, v123
	v_add_f32_e32 v167, v196, v123
	v_add_f32_e32 v168, v197, v123
	v_add_f32_e32 v169, v198, v123
	v_add_f32_e32 v170, v199, v123
	v_add_f32_e32 v171, v200, v123
	v_add_f32_e32 v172, v201, v123
	v_add_f32_e32 v173, v202, v123
	s_waitcnt lgkmcnt(0)
	s_nop 1
	v_mfma_f32_32x32x16_bf16 v[158:173], v[50:53], v[82:85], v[158:173]
	v_mfma_f32_32x32x16_bf16 v[158:173], v[54:57], v[86:89], v[158:173]
	v_mfma_f32_32x32x16_bf16 v[158:173], v[58:61], v[90:93], v[158:173]
	v_mfma_f32_32x32x16_bf16 v[158:173], v[62:65], v[94:97], v[158:173]
	s_add_i32 s52, s54, 2
	s_and_b32 s53, s52, 1
	s_lshr_b32 s52, s52, 1
	s_sub_i32 s52, s52, s59
	s_lshl_b32 s52, s52, 14
	s_lshl_b32 s53, s53, 12
	s_add_i32 s56, s53, s52
	v_add_u32_e32 v140, s56, v124
	v_add_u32_e32 v142, s56, v134
	v_add_u32_e32 v143, s56, v135
	v_add_u32_e32 v144, s56, v136
	ds_read_b128 v[50:53], v140
	ds_read_b128 v[54:57], v142
	ds_read_b128 v[58:61], v143
	ds_read_b128 v[62:65], v144
	v_max3_f32 v145, v34, v35, v36
	v_max3_f32 v146, v37, v38, v39
	v_max3_f32 v145, v145, v40, v41
	v_max3_f32 v146, v146, v42, v43
	v_max3_f32 v145, v145, v44, v45
	v_max3_f32 v146, v146, v46, v47
	v_max3_f32 v145, v145, v48, v49
	v_max_f32_e32 v145, v145, v146
	v_mov_b32_e32 v146, v145
	s_nop 1
	v_permlane32_swap_b32_e32 v145, v146
	v_max_f32_e32 v145, v145, v146
	s_cmp_lg_u32 s63, 0
	s_cbranch_scc1 .Ld3_first0
	v_cmp_lt_f32_e32 vcc, s73, v145
	s_cbranch_vccz .Ld3_exp0
	v_max_f32_e32 v147, 0, v145
	v_exp_f32_e64 v148, -v147
	v_add_f32_e32 v138, v138, v147
	v_sub_f32_e32 v34, v34, v147
	v_sub_f32_e32 v35, v35, v147
	v_sub_f32_e32 v36, v36, v147
	v_sub_f32_e32 v37, v37, v147
	v_sub_f32_e32 v38, v38, v147
	v_sub_f32_e32 v39, v39, v147
	v_sub_f32_e32 v40, v40, v147
	v_sub_f32_e32 v41, v41, v147
	v_sub_f32_e32 v42, v42, v147
	v_sub_f32_e32 v43, v43, v147
	v_sub_f32_e32 v44, v44, v147
	v_sub_f32_e32 v45, v45, v147
	v_sub_f32_e32 v46, v46, v147
	v_sub_f32_e32 v47, v47, v147
	v_sub_f32_e32 v48, v48, v147
	v_sub_f32_e32 v49, v49, v147
	v_mul_f32_e32 v2, v2, v148
	v_mul_f32_e32 v3, v3, v148
	v_mul_f32_e32 v4, v4, v148
	v_mul_f32_e32 v5, v5, v148
	v_mul_f32_e32 v6, v6, v148
	v_mul_f32_e32 v7, v7, v148
	v_mul_f32_e32 v8, v8, v148
	v_mul_f32_e32 v9, v9, v148
	v_mul_f32_e32 v10, v10, v148
	v_mul_f32_e32 v11, v11, v148
	v_mul_f32_e32 v12, v12, v148
	v_mul_f32_e32 v13, v13, v148
	v_mul_f32_e32 v14, v14, v148
	v_mul_f32_e32 v15, v15, v148
	v_mul_f32_e32 v16, v16, v148
	v_mul_f32_e32 v17, v17, v148
	v_mul_f32_e32 v18, v18, v148
	v_mul_f32_e32 v19, v19, v148
	v_mul_f32_e32 v20, v20, v148
	v_mul_f32_e32 v21, v21, v148
	v_mul_f32_e32 v22, v22, v148
	v_mul_f32_e32 v23, v23, v148
	v_mul_f32_e32 v24, v24, v148
	v_mul_f32_e32 v25, v25, v148
	v_mul_f32_e32 v26, v26, v148
	v_mul_f32_e32 v27, v27, v148
	v_mul_f32_e32 v28, v28, v148
	v_mul_f32_e32 v29, v29, v148
	v_mul_f32_e32 v30, v30, v148
	v_mul_f32_e32 v31, v31, v148
	v_mul_f32_e32 v32, v32, v148
	v_mul_f32_e32 v33, v33, v148
	v_mul_f32_e32 v139, v139, v148
	s_nop 7
	s_nop 7
	v_sub_f32_e32 v158, v158, v147
	v_sub_f32_e32 v159, v159, v147
	v_sub_f32_e32 v160, v160, v147
	v_sub_f32_e32 v161, v161, v147
	v_sub_f32_e32 v162, v162, v147
	v_sub_f32_e32 v163, v163, v147
	v_sub_f32_e32 v164, v164, v147
	v_sub_f32_e32 v165, v165, v147
	v_sub_f32_e32 v166, v166, v147
	v_sub_f32_e32 v167, v167, v147
	v_sub_f32_e32 v168, v168, v147
	v_sub_f32_e32 v169, v169, v147
	v_sub_f32_e32 v170, v170, v147
	v_sub_f32_e32 v171, v171, v147
	v_sub_f32_e32 v172, v172, v147
	v_sub_f32_e32 v173, v173, v147
	s_branch .Ld3_exp0
.Ld3_first0:
	s_mov_b32 s63, 0
	v_add_f32_e32 v138, v138, v145
	v_sub_f32_e32 v34, v34, v145
	v_sub_f32_e32 v35, v35, v145
	v_sub_f32_e32 v36, v36, v145
	v_sub_f32_e32 v37, v37, v145
	v_sub_f32_e32 v38, v38, v145
	v_sub_f32_e32 v39, v39, v145
	v_sub_f32_e32 v40, v40, v145
	v_sub_f32_e32 v41, v41, v145
	v_sub_f32_e32 v42, v42, v145
	v_sub_f32_e32 v43, v43, v145
	v_sub_f32_e32 v44, v44, v145
	v_sub_f32_e32 v45, v45, v145
	v_sub_f32_e32 v46, v46, v145
	v_sub_f32_e32 v47, v47, v145
	v_sub_f32_e32 v48, v48, v145
	v_sub_f32_e32 v49, v49, v145
	s_nop 7
	s_nop 7
	v_sub_f32_e32 v158, v158, v145
	v_sub_f32_e32 v159, v159, v145
	v_sub_f32_e32 v160, v160, v145
	v_sub_f32_e32 v161, v161, v145
	v_sub_f32_e32 v162, v162, v145
	v_sub_f32_e32 v163, v163, v145
	v_sub_f32_e32 v164, v164, v145
	v_sub_f32_e32 v165, v165, v145
	v_sub_f32_e32 v166, v166, v145
	v_sub_f32_e32 v167, v167, v145
	v_sub_f32_e32 v168, v168, v145
	v_sub_f32_e32 v169, v169, v145
	v_sub_f32_e32 v170, v170, v145
	v_sub_f32_e32 v171, v171, v145
	v_sub_f32_e32 v172, v172, v145
	v_sub_f32_e32 v173, v173, v145
.Ld3_exp0:
	v_exp_f32_e32 v34, v34
	v_exp_f32_e32 v35, v35
	v_exp_f32_e32 v36, v36
	v_exp_f32_e32 v37, v37
	v_exp_f32_e32 v38, v38
	v_exp_f32_e32 v39, v39
	v_exp_f32_e32 v40, v40
	v_exp_f32_e32 v41, v41
	v_exp_f32_e32 v42, v42
	v_exp_f32_e32 v43, v43
	v_exp_f32_e32 v44, v44
	v_exp_f32_e32 v45, v45
	v_exp_f32_e32 v46, v46
	v_exp_f32_e32 v47, v47
	v_exp_f32_e32 v48, v48
	v_exp_f32_e32 v49, v49
	v_add_f32_e32 v149, v34, v35
	v_add_f32_e32 v150, v36, v37
	v_add_f32_e32 v149, v149, v38
	v_add_f32_e32 v150, v150, v39
	v_add_f32_e32 v149, v149, v40
	v_add_f32_e32 v150, v150, v41
	v_add_f32_e32 v149, v149, v42
	v_add_f32_e32 v150, v150, v43
	v_add_f32_e32 v149, v149, v44
	v_add_f32_e32 v150, v150, v45
	v_add_f32_e32 v149, v149, v46
	v_add_f32_e32 v150, v150, v47
	v_add_f32_e32 v149, v149, v48
	v_add_f32_e32 v150, v150, v49
	v_add_f32_e32 v149, v149, v150
	v_add_f32_e32 v139, v139, v149
	v_cvt_pk_bf16_f32 v114, v34, v35
	v_cvt_pk_bf16_f32 v115, v36, v37
	v_cvt_pk_bf16_f32 v116, v38, v39
	v_cvt_pk_bf16_f32 v117, v40, v41
	v_cvt_pk_bf16_f32 v118, v42, v43
	v_cvt_pk_bf16_f32 v119, v44, v45
	v_cvt_pk_bf16_f32 v120, v46, v47
	v_cvt_pk_bf16_f32 v121, v48, v49
	s_waitcnt lgkmcnt(4)
	s_nop 1
	v_mfma_f32_32x32x16_bf16 v[18:33], v[98:101], v[114:117], v[18:33]
	v_mfma_f32_32x32x16_bf16 v[2:17], v[106:109], v[114:117], v[2:17]
	v_mfma_f32_32x32x16_bf16 v[18:33], v[102:105], v[118:121], v[18:33]
	v_mfma_f32_32x32x16_bf16 v[2:17], v[110:113], v[118:121], v[2:17]
	s_add_i32 s52, s54, 1
	s_and_b32 s53, s52, 1
	s_lshr_b32 s52, s52, 1
	s_sub_i32 s52, s52, s59
	s_lshl_b32 s52, s52, 14
	s_lshl_b32 s53, s53, 11
	s_add_i32 s53, s53, s52
	s_addk_i32 s53, 0x2000
	v_add_u32_e32 v141, s53, v125
	ds_read_b64_tr_b16 v[98:99], v141
	ds_read_b64_tr_b16 v[100:101], v141 offset:512
	ds_read_b64_tr_b16 v[102:103], v141 offset:1024
	ds_read_b64_tr_b16 v[104:105], v141 offset:1536
	ds_read_b64_tr_b16 v[106:107], v141 offset:4096
	ds_read_b64_tr_b16 v[108:109], v141 offset:4608
	ds_read_b64_tr_b16 v[110:111], v141 offset:5120
	ds_read_b64_tr_b16 v[112:113], v141 offset:5632
.Ld3_b1:
	v_add_u32_e32 v140, 64, v122
	v_cvt_f32_i32_e32 v140, v140
	v_fma_f32 v123, -v126, v140, -v138
	v_add_f32_e32 v34, v187, v123
	v_add_f32_e32 v35, v188, v123
	v_add_f32_e32 v36, v189, v123
	v_add_f32_e32 v37, v190, v123
	v_add_f32_e32 v38, v191, v123
	v_add_f32_e32 v39, v192, v123
	v_add_f32_e32 v40, v193, v123
	v_add_f32_e32 v41, v194, v123
	v_add_f32_e32 v42, v195, v123
	v_add_f32_e32 v43, v196, v123
	v_add_f32_e32 v44, v197, v123
	v_add_f32_e32 v45, v198, v123
	v_add_f32_e32 v46, v199, v123
	v_add_f32_e32 v47, v200, v123
	v_add_f32_e32 v48, v201, v123
	v_add_f32_e32 v49, v202, v123
	s_waitcnt lgkmcnt(0)
	s_nop 1
	v_mfma_f32_32x32x16_bf16 v[34:49], v[50:53], v[82:85], v[34:49]
	v_mfma_f32_32x32x16_bf16 v[34:49], v[54:57], v[86:89], v[34:49]
	v_mfma_f32_32x32x16_bf16 v[34:49], v[58:61], v[90:93], v[34:49]
	v_mfma_f32_32x32x16_bf16 v[34:49], v[62:65], v[94:97], v[34:49]
	s_add_i32 s52, s54, 3
	s_and_b32 s53, s52, 1
	s_lshr_b32 s52, s52, 1
	s_sub_i32 s52, s52, s59
	s_lshl_b32 s52, s52, 14
	s_lshl_b32 s53, s53, 12
	s_add_i32 s56, s53, s52
	v_add_u32_e32 v140, s56, v124
	v_add_u32_e32 v142, s56, v134
	v_add_u32_e32 v143, s56, v135
	v_add_u32_e32 v144, s56, v136
	ds_read_b128 v[50:53], v140
	ds_read_b128 v[54:57], v142
	ds_read_b128 v[58:61], v143
	ds_read_b128 v[62:65], v144
	v_max3_f32 v145, v158, v159, v160
	v_max3_f32 v146, v161, v162, v163
	v_max3_f32 v145, v145, v164, v165
	v_max3_f32 v146, v146, v166, v167
	v_max3_f32 v145, v145, v168, v169
	v_max3_f32 v146, v146, v170, v171
	v_max3_f32 v145, v145, v172, v173
	v_max_f32_e32 v145, v145, v146
	v_mov_b32_e32 v146, v145
	s_nop 1
	v_permlane32_swap_b32_e32 v145, v146
	v_max_f32_e32 v145, v145, v146
	s_cmp_lg_u32 s63, 0
	s_cbranch_scc1 .Ld3_first1
	v_cmp_lt_f32_e32 vcc, s73, v145
	s_cbranch_vccz .Ld3_exp1
	v_max_f32_e32 v147, 0, v145
	v_exp_f32_e64 v148, -v147
	v_add_f32_e32 v138, v138, v147
	v_sub_f32_e32 v158, v158, v147
	v_sub_f32_e32 v159, v159, v147
	v_sub_f32_e32 v160, v160, v147
	v_sub_f32_e32 v161, v161, v147
	v_sub_f32_e32 v162, v162, v147
	v_sub_f32_e32 v163, v163, v147
	v_sub_f32_e32 v164, v164, v147
	v_sub_f32_e32 v165, v165, v147
	v_sub_f32_e32 v166, v166, v147
	v_sub_f32_e32 v167, v167, v147
	v_sub_f32_e32 v168, v168, v147
	v_sub_f32_e32 v169, v169, v147
	v_sub_f32_e32 v170, v170, v147
	v_sub_f32_e32 v171, v171, v147
	v_sub_f32_e32 v172, v172, v147
	v_sub_f32_e32 v173, v173, v147
	v_mul_f32_e32 v2, v2, v148
	v_mul_f32_e32 v3, v3, v148
	v_mul_f32_e32 v4, v4, v148
	v_mul_f32_e32 v5, v5, v148
	v_mul_f32_e32 v6, v6, v148
	v_mul_f32_e32 v7, v7, v148
	v_mul_f32_e32 v8, v8, v148
	v_mul_f32_e32 v9, v9, v148
	v_mul_f32_e32 v10, v10, v148
	v_mul_f32_e32 v11, v11, v148
	v_mul_f32_e32 v12, v12, v148
	v_mul_f32_e32 v13, v13, v148
	v_mul_f32_e32 v14, v14, v148
	v_mul_f32_e32 v15, v15, v148
	v_mul_f32_e32 v16, v16, v148
	v_mul_f32_e32 v17, v17, v148
	v_mul_f32_e32 v18, v18, v148
	v_mul_f32_e32 v19, v19, v148
	v_mul_f32_e32 v20, v20, v148
	v_mul_f32_e32 v21, v21, v148
	v_mul_f32_e32 v22, v22, v148
	v_mul_f32_e32 v23, v23, v148
	v_mul_f32_e32 v24, v24, v148
	v_mul_f32_e32 v25, v25, v148
	v_mul_f32_e32 v26, v26, v148
	v_mul_f32_e32 v27, v27, v148
	v_mul_f32_e32 v28, v28, v148
	v_mul_f32_e32 v29, v29, v148
	v_mul_f32_e32 v30, v30, v148
	v_mul_f32_e32 v31, v31, v148
	v_mul_f32_e32 v32, v32, v148
	v_mul_f32_e32 v33, v33, v148
	v_mul_f32_e32 v139, v139, v148
	s_nop 7
	s_nop 7
	v_sub_f32_e32 v34, v34, v147
	v_sub_f32_e32 v35, v35, v147
	v_sub_f32_e32 v36, v36, v147
	v_sub_f32_e32 v37, v37, v147
	v_sub_f32_e32 v38, v38, v147
	v_sub_f32_e32 v39, v39, v147
	v_sub_f32_e32 v40, v40, v147
	v_sub_f32_e32 v41, v41, v147
	v_sub_f32_e32 v42, v42, v147
	v_sub_f32_e32 v43, v43, v147
	v_sub_f32_e32 v44, v44, v147
	v_sub_f32_e32 v45, v45, v147
	v_sub_f32_e32 v46, v46, v147
	v_sub_f32_e32 v47, v47, v147
	v_sub_f32_e32 v48, v48, v147
	v_sub_f32_e32 v49, v49, v147
	s_branch .Ld3_exp1
.Ld3_first1:
	s_mov_b32 s63, 0
	v_add_f32_e32 v138, v138, v145
	v_sub_f32_e32 v158, v158, v145
	v_sub_f32_e32 v159, v159, v145
	v_sub_f32_e32 v160, v160, v145
	v_sub_f32_e32 v161, v161, v145
	v_sub_f32_e32 v162, v162, v145
	v_sub_f32_e32 v163, v163, v145
	v_sub_f32_e32 v164, v164, v145
	v_sub_f32_e32 v165, v165, v145
	v_sub_f32_e32 v166, v166, v145
	v_sub_f32_e32 v167, v167, v145
	v_sub_f32_e32 v168, v168, v145
	v_sub_f32_e32 v169, v169, v145
	v_sub_f32_e32 v170, v170, v145
	v_sub_f32_e32 v171, v171, v145
	v_sub_f32_e32 v172, v172, v145
	v_sub_f32_e32 v173, v173, v145
	s_nop 7
	s_nop 7
	v_sub_f32_e32 v34, v34, v145
	v_sub_f32_e32 v35, v35, v145
	v_sub_f32_e32 v36, v36, v145
	v_sub_f32_e32 v37, v37, v145
	v_sub_f32_e32 v38, v38, v145
	v_sub_f32_e32 v39, v39, v145
	v_sub_f32_e32 v40, v40, v145
	v_sub_f32_e32 v41, v41, v145
	v_sub_f32_e32 v42, v42, v145
	v_sub_f32_e32 v43, v43, v145
	v_sub_f32_e32 v44, v44, v145
	v_sub_f32_e32 v45, v45, v145
	v_sub_f32_e32 v46, v46, v145
	v_sub_f32_e32 v47, v47, v145
	v_sub_f32_e32 v48, v48, v145
	v_sub_f32_e32 v49, v49, v145
.Ld3_exp1:
	v_exp_f32_e32 v158, v158
	v_exp_f32_e32 v159, v159
	v_exp_f32_e32 v160, v160
	v_exp_f32_e32 v161, v161
	v_exp_f32_e32 v162, v162
	v_exp_f32_e32 v163, v163
	v_exp_f32_e32 v164, v164
	v_exp_f32_e32 v165, v165
	v_exp_f32_e32 v166, v166
	v_exp_f32_e32 v167, v167
	v_exp_f32_e32 v168, v168
	v_exp_f32_e32 v169, v169
	v_exp_f32_e32 v170, v170
	v_exp_f32_e32 v171, v171
	v_exp_f32_e32 v172, v172
	v_exp_f32_e32 v173, v173
	v_add_f32_e32 v149, v158, v159
	v_add_f32_e32 v150, v160, v161
	v_add_f32_e32 v149, v149, v162
	v_add_f32_e32 v150, v150, v163
	v_add_f32_e32 v149, v149, v164
	v_add_f32_e32 v150, v150, v165
	v_add_f32_e32 v149, v149, v166
	v_add_f32_e32 v150, v150, v167
	v_add_f32_e32 v149, v149, v168
	v_add_f32_e32 v150, v150, v169
	v_add_f32_e32 v149, v149, v170
	v_add_f32_e32 v150, v150, v171
	v_add_f32_e32 v149, v149, v172
	v_add_f32_e32 v150, v150, v173
	v_add_f32_e32 v149, v149, v150
	v_add_f32_e32 v139, v139, v149
	v_cvt_pk_bf16_f32 v114, v158, v159
	v_cvt_pk_bf16_f32 v115, v160, v161
	v_cvt_pk_bf16_f32 v116, v162, v163
	v_cvt_pk_bf16_f32 v117, v164, v165
	v_cvt_pk_bf16_f32 v118, v166, v167
	v_cvt_pk_bf16_f32 v119, v168, v169
	v_cvt_pk_bf16_f32 v120, v170, v171
	v_cvt_pk_bf16_f32 v121, v172, v173
	s_waitcnt lgkmcnt(4)
	s_nop 1
	v_mfma_f32_32x32x16_bf16 v[18:33], v[98:101], v[114:117], v[18:33]
	v_mfma_f32_32x32x16_bf16 v[2:17], v[106:109], v[114:117], v[2:17]
	v_mfma_f32_32x32x16_bf16 v[18:33], v[102:105], v[118:121], v[18:33]
	v_mfma_f32_32x32x16_bf16 v[2:17], v[110:113], v[118:121], v[2:17]
	s_add_i32 s52, s54, 2
	s_and_b32 s53, s52, 1
	s_lshr_b32 s52, s52, 1
	s_sub_i32 s52, s52, s59
	s_lshl_b32 s52, s52, 14
	s_lshl_b32 s53, s53, 11
	s_add_i32 s53, s53, s52
	s_addk_i32 s53, 0x2000
	v_add_u32_e32 v141, s53, v125
	ds_read_b64_tr_b16 v[98:99], v141
	ds_read_b64_tr_b16 v[100:101], v141 offset:512
	ds_read_b64_tr_b16 v[102:103], v141 offset:1024
	ds_read_b64_tr_b16 v[104:105], v141 offset:1536
	ds_read_b64_tr_b16 v[106:107], v141 offset:4096
	ds_read_b64_tr_b16 v[108:109], v141 offset:4608
	ds_read_b64_tr_b16 v[110:111], v141 offset:5120
	ds_read_b64_tr_b16 v[112:113], v141 offset:5632
.Ld3_b2:
	v_add_u32_e32 v140, 32, v122
	v_cvt_f32_i32_e32 v140, v140
	v_fma_f32 v123, -v126, v140, -v138
	v_add_f32_e32 v158, v187, v123
	v_add_f32_e32 v159, v188, v123
	v_add_f32_e32 v160, v189, v123
	v_add_f32_e32 v161, v190, v123
	v_add_f32_e32 v162, v191, v123
	v_add_f32_e32 v163, v192, v123
	v_add_f32_e32 v164, v193, v123
	v_add_f32_e32 v165, v194, v123
	v_add_f32_e32 v166, v195, v123
	v_add_f32_e32 v167, v196, v123
	v_add_f32_e32 v168, v197, v123
	v_add_f32_e32 v169, v198, v123
	v_add_f32_e32 v170, v199, v123
	v_add_f32_e32 v171, v200, v123
	v_add_f32_e32 v172, v201, v123
	v_add_f32_e32 v173, v202, v123
	s_waitcnt lgkmcnt(0)
	s_nop 1
	v_mfma_f32_32x32x16_bf16 v[158:173], v[50:53], v[82:85], v[158:173]
	v_mfma_f32_32x32x16_bf16 v[158:173], v[54:57], v[86:89], v[158:173]
	v_mfma_f32_32x32x16_bf16 v[158:173], v[58:61], v[90:93], v[158:173]
	v_mfma_f32_32x32x16_bf16 v[158:173], v[62:65], v[94:97], v[158:173]
	s_add_i32 s52, s54, 4
	s_and_b32 s53, s52, 1
	s_lshr_b32 s52, s52, 1
	s_sub_i32 s52, s52, s59
	s_lshl_b32 s52, s52, 14
	s_lshl_b32 s53, s53, 12
	s_add_i32 s56, s53, s52
	v_add_u32_e32 v140, s56, v124
	v_add_u32_e32 v142, s56, v134
	v_add_u32_e32 v143, s56, v135
	v_add_u32_e32 v144, s56, v136
	ds_read_b128 v[50:53], v140
	ds_read_b128 v[54:57], v142
	ds_read_b128 v[58:61], v143
	ds_read_b128 v[62:65], v144
	v_max3_f32 v145, v34, v35, v36
	v_max3_f32 v146, v37, v38, v39
	v_max3_f32 v145, v145, v40, v41
	v_max3_f32 v146, v146, v42, v43
	v_max3_f32 v145, v145, v44, v45
	v_max3_f32 v146, v146, v46, v47
	v_max3_f32 v145, v145, v48, v49
	v_max_f32_e32 v145, v145, v146
	v_mov_b32_e32 v146, v145
	s_nop 1
	v_permlane32_swap_b32_e32 v145, v146
	v_max_f32_e32 v145, v145, v146
	s_cmp_lg_u32 s63, 0
	s_cbranch_scc1 .Ld3_first2
	v_cmp_lt_f32_e32 vcc, s73, v145
	s_cbranch_vccz .Ld3_exp2
	v_max_f32_e32 v147, 0, v145
	v_exp_f32_e64 v148, -v147
	v_add_f32_e32 v138, v138, v147
	v_sub_f32_e32 v34, v34, v147
	v_sub_f32_e32 v35, v35, v147
	v_sub_f32_e32 v36, v36, v147
	v_sub_f32_e32 v37, v37, v147
	v_sub_f32_e32 v38, v38, v147
	v_sub_f32_e32 v39, v39, v147
	v_sub_f32_e32 v40, v40, v147
	v_sub_f32_e32 v41, v41, v147
	v_sub_f32_e32 v42, v42, v147
	v_sub_f32_e32 v43, v43, v147
	v_sub_f32_e32 v44, v44, v147
	v_sub_f32_e32 v45, v45, v147
	v_sub_f32_e32 v46, v46, v147
	v_sub_f32_e32 v47, v47, v147
	v_sub_f32_e32 v48, v48, v147
	v_sub_f32_e32 v49, v49, v147
	v_mul_f32_e32 v2, v2, v148
	v_mul_f32_e32 v3, v3, v148
	v_mul_f32_e32 v4, v4, v148
	v_mul_f32_e32 v5, v5, v148
	v_mul_f32_e32 v6, v6, v148
	v_mul_f32_e32 v7, v7, v148
	v_mul_f32_e32 v8, v8, v148
	v_mul_f32_e32 v9, v9, v148
	v_mul_f32_e32 v10, v10, v148
	v_mul_f32_e32 v11, v11, v148
	v_mul_f32_e32 v12, v12, v148
	v_mul_f32_e32 v13, v13, v148
	v_mul_f32_e32 v14, v14, v148
	v_mul_f32_e32 v15, v15, v148
	v_mul_f32_e32 v16, v16, v148
	v_mul_f32_e32 v17, v17, v148
	v_mul_f32_e32 v18, v18, v148
	v_mul_f32_e32 v19, v19, v148
	v_mul_f32_e32 v20, v20, v148
	v_mul_f32_e32 v21, v21, v148
	v_mul_f32_e32 v22, v22, v148
	v_mul_f32_e32 v23, v23, v148
	v_mul_f32_e32 v24, v24, v148
	v_mul_f32_e32 v25, v25, v148
	v_mul_f32_e32 v26, v26, v148
	v_mul_f32_e32 v27, v27, v148
	v_mul_f32_e32 v28, v28, v148
	v_mul_f32_e32 v29, v29, v148
	v_mul_f32_e32 v30, v30, v148
	v_mul_f32_e32 v31, v31, v148
	v_mul_f32_e32 v32, v32, v148
	v_mul_f32_e32 v33, v33, v148
	v_mul_f32_e32 v139, v139, v148
	s_nop 7
	s_nop 7
	v_sub_f32_e32 v158, v158, v147
	v_sub_f32_e32 v159, v159, v147
	v_sub_f32_e32 v160, v160, v147
	v_sub_f32_e32 v161, v161, v147
	v_sub_f32_e32 v162, v162, v147
	v_sub_f32_e32 v163, v163, v147
	v_sub_f32_e32 v164, v164, v147
	v_sub_f32_e32 v165, v165, v147
	v_sub_f32_e32 v166, v166, v147
	v_sub_f32_e32 v167, v167, v147
	v_sub_f32_e32 v168, v168, v147
	v_sub_f32_e32 v169, v169, v147
	v_sub_f32_e32 v170, v170, v147
	v_sub_f32_e32 v171, v171, v147
	v_sub_f32_e32 v172, v172, v147
	v_sub_f32_e32 v173, v173, v147
	s_branch .Ld3_exp2

.Ld3_exp2:
	v_exp_f32_e32 v34, v34
	v_exp_f32_e32 v35, v35
	v_exp_f32_e32 v36, v36
	v_exp_f32_e32 v37, v37
	v_exp_f32_e32 v38, v38
	v_exp_f32_e32 v39, v39
	v_exp_f32_e32 v40, v40
	v_exp_f32_e32 v41, v41
	v_exp_f32_e32 v42, v42
	v_exp_f32_e32 v43, v43
	v_exp_f32_e32 v44, v44
	v_exp_f32_e32 v45, v45
	v_exp_f32_e32 v46, v46
	v_exp_f32_e32 v47, v47
	v_exp_f32_e32 v48, v48
	v_exp_f32_e32 v49, v49
	v_add_f32_e32 v149, v34, v35
	v_add_f32_e32 v150, v36, v37
	v_add_f32_e32 v149, v149, v38
	v_add_f32_e32 v150, v150, v39
	v_add_f32_e32 v149, v149, v40
	v_add_f32_e32 v150, v150, v41
	v_add_f32_e32 v149, v149, v42
	v_add_f32_e32 v150, v150, v43
	v_add_f32_e32 v149, v149, v44
	v_add_f32_e32 v150, v150, v45
	v_add_f32_e32 v149, v149, v46
	v_add_f32_e32 v150, v150, v47
	v_add_f32_e32 v149, v149, v48
	v_add_f32_e32 v150, v150, v49
	v_add_f32_e32 v149, v149, v150
	v_add_f32_e32 v139, v139, v149
	v_cvt_pk_bf16_f32 v114, v34, v35
	v_cvt_pk_bf16_f32 v115, v36, v37
	v_cvt_pk_bf16_f32 v116, v38, v39
	v_cvt_pk_bf16_f32 v117, v40, v41
	v_cvt_pk_bf16_f32 v118, v42, v43
	v_cvt_pk_bf16_f32 v119, v44, v45
	v_cvt_pk_bf16_f32 v120, v46, v47
	v_cvt_pk_bf16_f32 v121, v48, v49
	s_waitcnt lgkmcnt(4)
	s_nop 1
	v_mfma_f32_32x32x16_bf16 v[18:33], v[98:101], v[114:117], v[18:33]
	v_mfma_f32_32x32x16_bf16 v[2:17], v[106:109], v[114:117], v[2:17]
	v_mfma_f32_32x32x16_bf16 v[18:33], v[102:105], v[118:121], v[18:33]
	v_mfma_f32_32x32x16_bf16 v[2:17], v[110:113], v[118:121], v[2:17]
	s_add_i32 s52, s54, 3
	s_and_b32 s53, s52, 1
	s_lshr_b32 s52, s52, 1
	s_sub_i32 s52, s52, s59
	s_lshl_b32 s52, s52, 14
	s_lshl_b32 s53, s53, 11
	s_add_i32 s53, s53, s52
	s_addk_i32 s53, 0x2000
	v_add_u32_e32 v141, s53, v125
	ds_read_b64_tr_b16 v[98:99], v141
	ds_read_b64_tr_b16 v[100:101], v141 offset:512
	ds_read_b64_tr_b16 v[102:103], v141 offset:1024
	ds_read_b64_tr_b16 v[104:105], v141 offset:1536
	ds_read_b64_tr_b16 v[106:107], v141 offset:4096
	ds_read_b64_tr_b16 v[108:109], v141 offset:4608
	ds_read_b64_tr_b16 v[110:111], v141 offset:5120
	ds_read_b64_tr_b16 v[112:113], v141 offset:5632
.Ld3_b3:
	v_add_u32_e32 v140, 0, v122
	v_cvt_f32_i32_e32 v140, v140
	v_fma_f32 v123, -v126, v140, -v138
	v_add_f32_e32 v34, v219, v123
	v_add_f32_e32 v35, v220, v123
	v_add_f32_e32 v36, v221, v123
	v_add_f32_e32 v37, v222, v123
	v_add_f32_e32 v38, v223, v123
	v_add_f32_e32 v39, v224, v123
	v_add_f32_e32 v40, v225, v123
	v_add_f32_e32 v41, v226, v123
	v_add_f32_e32 v42, v227, v123
	v_add_f32_e32 v43, v228, v123
	v_add_f32_e32 v44, v229, v123
	v_add_f32_e32 v45, v230, v123
	v_add_f32_e32 v46, v231, v123
	v_add_f32_e32 v47, v232, v123
	v_add_f32_e32 v48, v233, v123
	v_add_f32_e32 v49, v234, v123
	s_waitcnt lgkmcnt(0)
	s_nop 1
	v_mfma_f32_32x32x16_bf16 v[34:49], v[50:53], v[82:85], v[34:49]
	v_mfma_f32_32x32x16_bf16 v[34:49], v[54:57], v[86:89], v[34:49]
	v_mfma_f32_32x32x16_bf16 v[34:49], v[58:61], v[90:93], v[34:49]
	v_mfma_f32_32x32x16_bf16 v[34:49], v[62:65], v[94:97], v[34:49]
	v_max3_f32 v145, v158, v159, v160
	v_max3_f32 v146, v161, v162, v163
	v_max3_f32 v145, v145, v164, v165
	v_max3_f32 v146, v146, v166, v167
	v_max3_f32 v145, v145, v168, v169
	v_max3_f32 v146, v146, v170, v171
	v_max3_f32 v145, v145, v172, v173
	v_max_f32_e32 v145, v145, v146
	v_mov_b32_e32 v146, v145
	s_nop 1
	v_permlane32_swap_b32_e32 v145, v146
	v_max_f32_e32 v145, v145, v146
	s_cmp_lg_u32 s63, 0
	s_cbranch_scc1 .Ld3_first3
	v_cmp_lt_f32_e32 vcc, s73, v145
	s_cbranch_vccz .Ld3_exp3
	v_max_f32_e32 v147, 0, v145
	v_exp_f32_e64 v148, -v147
	v_add_f32_e32 v138, v138, v147
	v_sub_f32_e32 v158, v158, v147
	v_sub_f32_e32 v159, v159, v147
	v_sub_f32_e32 v160, v160, v147
	v_sub_f32_e32 v161, v161, v147
	v_sub_f32_e32 v162, v162, v147
	v_sub_f32_e32 v163, v163, v147
	v_sub_f32_e32 v164, v164, v147
	v_sub_f32_e32 v165, v165, v147
	v_sub_f32_e32 v166, v166, v147
	v_sub_f32_e32 v167, v167, v147
	v_sub_f32_e32 v168, v168, v147
	v_sub_f32_e32 v169, v169, v147
	v_sub_f32_e32 v170, v170, v147
	v_sub_f32_e32 v171, v171, v147
	v_sub_f32_e32 v172, v172, v147
	v_sub_f32_e32 v173, v173, v147
	v_mul_f32_e32 v2, v2, v148
	v_mul_f32_e32 v3, v3, v148
	v_mul_f32_e32 v4, v4, v148
	v_mul_f32_e32 v5, v5, v148
	v_mul_f32_e32 v6, v6, v148
	v_mul_f32_e32 v7, v7, v148
	v_mul_f32_e32 v8, v8, v148
	v_mul_f32_e32 v9, v9, v148
	v_mul_f32_e32 v10, v10, v148
	v_mul_f32_e32 v11, v11, v148
	v_mul_f32_e32 v12, v12, v148
	v_mul_f32_e32 v13, v13, v148
	v_mul_f32_e32 v14, v14, v148
	v_mul_f32_e32 v15, v15, v148
	v_mul_f32_e32 v16, v16, v148
	v_mul_f32_e32 v17, v17, v148
	v_mul_f32_e32 v18, v18, v148
	v_mul_f32_e32 v19, v19, v148
	v_mul_f32_e32 v20, v20, v148
	v_mul_f32_e32 v21, v21, v148
	v_mul_f32_e32 v22, v22, v148
	v_mul_f32_e32 v23, v23, v148
	v_mul_f32_e32 v24, v24, v148
	v_mul_f32_e32 v25, v25, v148
	v_mul_f32_e32 v26, v26, v148
	v_mul_f32_e32 v27, v27, v148
	v_mul_f32_e32 v28, v28, v148
	v_mul_f32_e32 v29, v29, v148
	v_mul_f32_e32 v30, v30, v148
	v_mul_f32_e32 v31, v31, v148
	v_mul_f32_e32 v32, v32, v148
	v_mul_f32_e32 v33, v33, v148
	v_mul_f32_e32 v139, v139, v148
	s_nop 7
	s_nop 7
	v_sub_f32_e32 v34, v34, v147
	v_sub_f32_e32 v35, v35, v147
	v_sub_f32_e32 v36, v36, v147
	v_sub_f32_e32 v37, v37, v147
	v_sub_f32_e32 v38, v38, v147
	v_sub_f32_e32 v39, v39, v147
	v_sub_f32_e32 v40, v40, v147
	v_sub_f32_e32 v41, v41, v147
	v_sub_f32_e32 v42, v42, v147
	v_sub_f32_e32 v43, v43, v147
	v_sub_f32_e32 v44, v44, v147
	v_sub_f32_e32 v45, v45, v147
	v_sub_f32_e32 v46, v46, v147
	v_sub_f32_e32 v47, v47, v147
	v_sub_f32_e32 v48, v48, v147
	v_sub_f32_e32 v49, v49, v147
	s_branch .Ld3_exp3

.Ld3_exp3:
	v_exp_f32_e32 v158, v158
	v_exp_f32_e32 v159, v159
	v_exp_f32_e32 v160, v160
	v_exp_f32_e32 v161, v161
	v_exp_f32_e32 v162, v162
	v_exp_f32_e32 v163, v163
	v_exp_f32_e32 v164, v164
	v_exp_f32_e32 v165, v165
	v_exp_f32_e32 v166, v166
	v_exp_f32_e32 v167, v167
	v_exp_f32_e32 v168, v168
	v_exp_f32_e32 v169, v169
	v_exp_f32_e32 v170, v170
	v_exp_f32_e32 v171, v171
	v_exp_f32_e32 v172, v172
	v_exp_f32_e32 v173, v173
	v_add_f32_e32 v149, v158, v159
	v_add_f32_e32 v150, v160, v161
	v_add_f32_e32 v149, v149, v162
	v_add_f32_e32 v150, v150, v163
	v_add_f32_e32 v149, v149, v164
	v_add_f32_e32 v150, v150, v165
	v_add_f32_e32 v149, v149, v166
	v_add_f32_e32 v150, v150, v167
	v_add_f32_e32 v149, v149, v168
	v_add_f32_e32 v150, v150, v169
	v_add_f32_e32 v149, v149, v170
	v_add_f32_e32 v150, v150, v171
	v_add_f32_e32 v149, v149, v172
	v_add_f32_e32 v150, v150, v173
	v_add_f32_e32 v149, v149, v150
	v_add_f32_e32 v139, v139, v149
	v_cvt_pk_bf16_f32 v114, v158, v159
	v_cvt_pk_bf16_f32 v115, v160, v161
	v_cvt_pk_bf16_f32 v116, v162, v163
	v_cvt_pk_bf16_f32 v117, v164, v165
	v_cvt_pk_bf16_f32 v118, v166, v167
	v_cvt_pk_bf16_f32 v119, v168, v169
	v_cvt_pk_bf16_f32 v120, v170, v171
	v_cvt_pk_bf16_f32 v121, v172, v173
	s_waitcnt lgkmcnt(0)
	s_nop 1
	v_mfma_f32_32x32x16_bf16 v[18:33], v[98:101], v[114:117], v[18:33]
	v_mfma_f32_32x32x16_bf16 v[2:17], v[106:109], v[114:117], v[2:17]
	v_mfma_f32_32x32x16_bf16 v[18:33], v[102:105], v[118:121], v[18:33]
	v_mfma_f32_32x32x16_bf16 v[2:17], v[110:113], v[118:121], v[2:17]
	s_add_i32 s52, s54, 4
	s_and_b32 s53, s52, 1
	s_lshr_b32 s52, s52, 1
	s_sub_i32 s52, s52, s59
	s_lshl_b32 s52, s52, 14
	s_lshl_b32 s53, s53, 11
	s_add_i32 s53, s53, s52
	s_addk_i32 s53, 0x2000
	v_add_u32_e32 v141, s53, v125
	ds_read_b64_tr_b16 v[98:99], v141
	ds_read_b64_tr_b16 v[100:101], v141 offset:512
	ds_read_b64_tr_b16 v[102:103], v141 offset:1024
	ds_read_b64_tr_b16 v[104:105], v141 offset:1536
	ds_read_b64_tr_b16 v[106:107], v141 offset:4096
	ds_read_b64_tr_b16 v[108:109], v141 offset:4608
	ds_read_b64_tr_b16 v[110:111], v141 offset:5120
	ds_read_b64_tr_b16 v[112:113], v141 offset:5632
.Ld3_b4:
	v_max3_f32 v145, v34, v35, v36
	v_max3_f32 v146, v37, v38, v39
	v_max3_f32 v145, v145, v40, v41
	v_max3_f32 v146, v146, v42, v43
	v_max3_f32 v145, v145, v44, v45
	v_max3_f32 v146, v146, v46, v47
	v_max3_f32 v145, v145, v48, v49
	v_max_f32_e32 v145, v145, v146
	v_mov_b32_e32 v146, v145
	s_nop 1
	v_permlane32_swap_b32_e32 v145, v146
	v_max_f32_e32 v145, v145, v146
	s_cmp_lg_u32 s63, 0
	s_cbranch_scc1 .Ld3_first4
	v_cmp_lt_f32_e32 vcc, s73, v145
	s_cbranch_vccz .Ld3_exp4
	v_max_f32_e32 v147, 0, v145
	v_exp_f32_e64 v148, -v147
	v_add_f32_e32 v138, v138, v147
	v_sub_f32_e32 v34, v34, v147
	v_sub_f32_e32 v35, v35, v147
	v_sub_f32_e32 v36, v36, v147
	v_sub_f32_e32 v37, v37, v147
	v_sub_f32_e32 v38, v38, v147
	v_sub_f32_e32 v39, v39, v147
	v_sub_f32_e32 v40, v40, v147
	v_sub_f32_e32 v41, v41, v147
	v_sub_f32_e32 v42, v42, v147
	v_sub_f32_e32 v43, v43, v147
	v_sub_f32_e32 v44, v44, v147
	v_sub_f32_e32 v45, v45, v147
	v_sub_f32_e32 v46, v46, v147
	v_sub_f32_e32 v47, v47, v147
	v_sub_f32_e32 v48, v48, v147
	v_sub_f32_e32 v49, v49, v147
	v_mul_f32_e32 v2, v2, v148
	v_mul_f32_e32 v3, v3, v148
	v_mul_f32_e32 v4, v4, v148
	v_mul_f32_e32 v5, v5, v148
	v_mul_f32_e32 v6, v6, v148
	v_mul_f32_e32 v7, v7, v148
	v_mul_f32_e32 v8, v8, v148
	v_mul_f32_e32 v9, v9, v148
	v_mul_f32_e32 v10, v10, v148
	v_mul_f32_e32 v11, v11, v148
	v_mul_f32_e32 v12, v12, v148
	v_mul_f32_e32 v13, v13, v148
	v_mul_f32_e32 v14, v14, v148
	v_mul_f32_e32 v15, v15, v148
	v_mul_f32_e32 v16, v16, v148
	v_mul_f32_e32 v17, v17, v148
	v_mul_f32_e32 v18, v18, v148
	v_mul_f32_e32 v19, v19, v148
	v_mul_f32_e32 v20, v20, v148
	v_mul_f32_e32 v21, v21, v148
	v_mul_f32_e32 v22, v22, v148
	v_mul_f32_e32 v23, v23, v148
	v_mul_f32_e32 v24, v24, v148
	v_mul_f32_e32 v25, v25, v148
	v_mul_f32_e32 v26, v26, v148
	v_mul_f32_e32 v27, v27, v148
	v_mul_f32_e32 v28, v28, v148
	v_mul_f32_e32 v29, v29, v148
	v_mul_f32_e32 v30, v30, v148
	v_mul_f32_e32 v31, v31, v148
	v_mul_f32_e32 v32, v32, v148
	v_mul_f32_e32 v33, v33, v148
	v_mul_f32_e32 v139, v139, v148
	s_branch .Ld3_exp4

.Ld3_exp4:
	v_exp_f32_e32 v34, v34
	v_exp_f32_e32 v35, v35
	v_exp_f32_e32 v36, v36
	v_exp_f32_e32 v37, v37
	v_exp_f32_e32 v38, v38
	v_exp_f32_e32 v39, v39
	v_exp_f32_e32 v40, v40
	v_exp_f32_e32 v41, v41
	v_exp_f32_e32 v42, v42
	v_exp_f32_e32 v43, v43
	v_exp_f32_e32 v44, v44
	v_exp_f32_e32 v45, v45
	v_exp_f32_e32 v46, v46
	v_exp_f32_e32 v47, v47
	v_exp_f32_e32 v48, v48
	v_exp_f32_e32 v49, v49
	v_add_f32_e32 v149, v34, v35
	v_add_f32_e32 v150, v36, v37
	v_add_f32_e32 v149, v149, v38
	v_add_f32_e32 v150, v150, v39
	v_add_f32_e32 v149, v149, v40
	v_add_f32_e32 v150, v150, v41
	v_add_f32_e32 v149, v149, v42
	v_add_f32_e32 v150, v150, v43
	v_add_f32_e32 v149, v149, v44
	v_add_f32_e32 v150, v150, v45
	v_add_f32_e32 v149, v149, v46
	v_add_f32_e32 v150, v150, v47
	v_add_f32_e32 v149, v149, v48
	v_add_f32_e32 v150, v150, v49
	v_add_f32_e32 v149, v149, v150
	v_add_f32_e32 v139, v139, v149
	v_cvt_pk_bf16_f32 v114, v34, v35
	v_cvt_pk_bf16_f32 v115, v36, v37
	v_cvt_pk_bf16_f32 v116, v38, v39
	v_cvt_pk_bf16_f32 v117, v40, v41
	v_cvt_pk_bf16_f32 v118, v42, v43
	v_cvt_pk_bf16_f32 v119, v44, v45
	v_cvt_pk_bf16_f32 v120, v46, v47
	v_cvt_pk_bf16_f32 v121, v48, v49
	s_waitcnt lgkmcnt(0)
	s_nop 1
	v_mfma_f32_32x32x16_bf16 v[18:33], v[98:101], v[114:117], v[18:33]
	v_mfma_f32_32x32x16_bf16 v[2:17], v[106:109], v[114:117], v[2:17]
	v_mfma_f32_32x32x16_bf16 v[18:33], v[102:105], v[118:121], v[18:33]
	v_mfma_f32_32x32x16_bf16 v[2:17], v[110:113], v[118:121], v[2:17]
	s_nop 7
	s_nop 7
